# grid barrier: the XCD leader (last local arriver) issues its L2/L1 invalidate beside its write-back, before the cross-XCD arrive, instead of after the release
# baseline (speedup 1.0000x reference)
.LBB0_329:
	s_or_b64 exec, exec, s[2:3]
	v_readlane_b32 s2, v254, 19
	v_readlane_b32 s3, v254, 20
	s_waitcnt vmcnt(0)
	s_nop 0
	s_nop 2
	global_atomic_add v3, v233, s[2:3]
	s_waitcnt vmcnt(0)

.LBB0_380:
	s_andn2_saveexec_b64 s[6:7], s[20:21]
	s_cbranch_execz .LBB0_398
	s_mov_b64 s[20:21], exec
	buffer_wbl2 sc1
	buffer_inv sc1
	s_waitcnt lgkmcnt(0)
	s_waitcnt vmcnt(0)
	v_mbcnt_lo_u32_b32 v1, s20, 0
	v_mbcnt_hi_u32_b32 v1, s21, v1
	v_cmp_eq_u32_e32 vcc, 0, v1
	s_and_saveexec_b64 s[22:23], vcc
	s_cbranch_execz .LBB0_383
	s_bcnt1_i32_b64 s5, s[20:21]
	v_readlane_b32 s6, v254, 21
	v_mov_b32_e32 v2, s5
	v_readlane_b32 s7, v254, 22
	s_nop 4
	global_atomic_add v2, v3, v2, s[6:7] sc0

.LBB0_397:
	s_or_b64 exec, exec, s[20:21]
	v_readlane_b32 s6, v254, 19
	v_readlane_b32 s7, v254, 20
	s_waitcnt vmcnt(0)
	s_nop 0
	s_nop 2
	global_atomic_add v3, v233, s[6:7]
	s_waitcnt vmcnt(0)

.LBB0_1320:
	s_andn2_saveexec_b64 s[2:3], s[2:3]
	s_cbranch_execz .LBB0_330
	s_mov_b64 s[2:3], exec
	buffer_wbl2 sc1
	buffer_inv sc1
	s_waitcnt lgkmcnt(0)
	s_waitcnt vmcnt(0)
	v_mbcnt_lo_u32_b32 v1, s2, 0
	v_mbcnt_hi_u32_b32 v1, s3, v1
	v_cmp_eq_u32_e32 vcc, 0, v1
	s_and_saveexec_b64 s[20:21], vcc
	s_cbranch_execz .LBB0_1323
	s_bcnt1_i32_b64 s2, s[2:3]
	v_mov_b32_e32 v2, s2
	v_readlane_b32 s2, v254, 21
	v_readlane_b32 s3, v254, 22
	s_nop 4
	global_atomic_add v2, v3, v2, s[2:3] sc0
